# DQK=64 fast path: no VALU before the first QK MFMA (all e0 adds moved behind MFMAs)
# baseline (speedup 1.0000x reference)
; __device__ __forceinline__ void finishSM(f32x16& p0, f32x16& p1, float alpha, float& l_reg, bf16x8& pa0, bf16x8& pa1, bf16x8& pa2, bf16x8& pa3) {
; #pragma unroll
;   for (int r = 0; r < 16; ++r) p1[r] = __builtin_amdgcn_exp2f(p1[r]);
;   float ps = 0;
; #pragma unroll
;   for (int r = 0; r < 16; ++r) ps += p0[r];
; #pragma unroll
;   for (int r = 0; r < 16; ++r) ps += p1[r];
;   { auto rr = __builtin_amdgcn_permlane32_swap(__float_as_uint(ps), __float_as_uint(ps), false, false);
;     ps = __uint_as_float(rr[0]) + __uint_as_float(rr[1]); }
;   l_reg = l_reg * alpha + ps;
;     ...
;   PK4(p0, 0, pa0); PK4(p0, 8, pa1); PK4(p1, 0, pa2); PK4(p1, 8, pa3);
;     ...
; }
; template <int DQK> __device__ __forceinline__ void qkt(f32x16& p0, f32x16& p1, const char* Ks, const bf16x8* qr, int r32, int hi, const f32x16& negm) {
; #pragma unroll
;   for (int d0 = 0; d0 < DQK / 16; ++d0) { const int cb = (d0 * 16 + hi * 8) * 2;
;     const bf16x8 b0 = *reinterpret_cast<const bf16x8*>(Ks + (DQK == 128 ? KSWZ(r32, cb) : KSWZ64(r32, cb)));
;     const bf16x8 b1 = *reinterpret_cast<const bf16x8*>(Ks + (DQK == 128 ? KSWZ(32 + r32, cb) : KSWZ64(32 + r32, cb)));
;     if (d0 == 0) { p0 = __builtin_amdgcn_mfma_f32_32x32x16_bf16(b0, qr[0], negm, 0, 0, 0); p1 = __builtin_amdgcn_mfma_f32_32x32x16_bf16(b1, qr[0], negm, 0, 0, 0); }
;     else { p0 = __builtin_amdgcn_mfma_f32_32x32x16_bf16(b0, qr[d0], p0, 0, 0, 0); p1 = __builtin_amdgcn_mfma_f32_32x32x16_bf16(b1, qr[d0], p1, 0, 0, 0); } }
; }
; __device__ __forceinline__ int v_st(int k, int c) { const int kk = (k & ~0xC) | ((k & 4) << 1) | ((k & 8) >> 1); return ((kk >> 3) * 4 + (c >> 5)) * 512 + ((kk & 7) * 32 + (c & 31)) * 2; }
; __device__ __forceinline__ int v_rd_base(int lane) { return ((lane & 3) << 3) | (((lane >> 2) & 3) << 6) | (((lane >> 4) & 1) << 5) | (((lane >> 5) & 1) << 8); }
; template <int OFF> __device__ __forceinline__ s16x4 tr_read(int vb) {
;   s16x4 r; asm volatile("ds_read_b64_tr_b16 %0, %1 offset:%2" : "=&v"(r) : "v"(vb), "i"(OFF) : "memory"); return r;
; }
; template <int D0> __device__ __forceinline__ void pv_one(f32x16& od, int vb, bf16x8 pa0, bf16x8 pa1, bf16x8 pa2, bf16x8 pa3) {
;   const s16x4 l0 = tr_read<v_rd_off(D0, 0, 0)>(vb), h0 = tr_read<v_rd_off(D0, 0, 1)>(vb), l1 = tr_read<v_rd_off(D0, 1, 0)>(vb), h1 = tr_read<v_rd_off(D0, 1, 1)>(vb);
.Lcret_f1:
	s_waitcnt lgkmcnt(4)
	v_mfma_f32_32x32x16_bf16 v[84:99], v[116:119], v[162:165], v[236:251]
	v_mfma_f32_32x32x16_bf16 v[116:131], v[180:183], v[162:165], v[236:251]
	ds_read_b128 v[180:183], v226 offset:53248
	v_add_f32_e32 v0, 0, v148
	v_add_f32_e32 v0, v178, v0
	v_add_f32_e32 v0, v146, v0
	v_add_f32_e32 v0, v149, v0
	v_add_f32_e32 v0, v144, v0
	v_add_f32_e32 v0, v147, v0
	v_add_f32_e32 v0, v143, v0
	v_add_f32_e32 v0, v145, v0
	v_add_f32_e32 v0, v137, v0
	v_add_f32_e32 v0, v139, v0
	s_waitcnt lgkmcnt(3)
	v_mfma_f32_32x32x16_bf16 v[116:131], v[184:187], v[158:161], v[116:131]
	v_add_f32_e32 v0, v136, v0
	v_add_f32_e32 v0, v138, v0
	v_add_f32_e32 v0, v135, v0
	v_add_f32_e32 v0, v142, v0
	v_add_f32_e32 v0, v140, v0
	v_add_f32_e32 v0, v141, v0
	v_mfma_f32_32x32x16_bf16 v[84:99], v[68:71], v[158:161], v[84:99]
	ds_read_b128 v[184:187], v226 offset:49152
	v_cvt_pk_bf16_f32 v76, v148, v178
	v_cvt_pk_bf16_f32 v77, v146, v149
	v_cvt_pk_bf16_f32 v78, v144, v147
	v_cvt_pk_bf16_f32 v79, v143, v145
	v_lshl_add_u64 v[148:149], v[194:195], 0, s[0:1]
	v_lshl_add_u64 v[196:197], v[192:193], 0, s[0:1]
	s_waitcnt lgkmcnt(2)
	v_mfma_f32_32x32x16_bf16 v[116:131], v[72:75], v[154:157], v[116:131]
	v_cvt_pk_bf16_f32 v80, v137, v139
	v_cvt_pk_bf16_f32 v81, v136, v138
	v_cvt_pk_bf16_f32 v82, v135, v142
	v_cvt_pk_bf16_f32 v83, v140, v141
	s_mov_b32 s4, 0x102b1000
	v_add_co_u32_e64 v132, s[4:5], s4, v148
	v_mfma_f32_32x32x16_bf16 v[84:99], v[206:209], v[154:157], v[84:99]
	ds_read_b64_tr_b16 v[134:135], v223 offset:0
	ds_read_b64_tr_b16 v[136:137], v223 offset:0x800
	ds_read_b64_tr_b16 v[138:139], v223 offset:0x200
	ds_read_b64_tr_b16 v[140:141], v223 offset:0xa00
	ds_read_b64_tr_b16 v[142:143], v223 offset:0x400
	ds_read_b64_tr_b16 v[144:145], v223 offset:0xc00
	ds_read_b64_tr_b16 v[198:199], v223 offset:0x600
	ds_read_b64_tr_b16 v[200:201], v223 offset:0xe00
	v_permlane32_swap_b32_e32 v76, v78
	v_permlane32_swap_b32_e32 v77, v79
	v_addc_co_u32_e64 v133, s[4:5], 0, v149, s[4:5]
	s_mov_b32 s4, 0x102f9000
	v_add_co_u32_e64 v202, s[4:5], s4, v148
	s_waitcnt lgkmcnt(8)
	v_mfma_f32_32x32x16_bf16 v[116:131], v[180:183], v[150:153], v[116:131]
	v_addc_co_u32_e64 v203, s[4:5], 0, v149, s[4:5]
	s_mov_b32 s4, 0x102b0000
	v_add_co_u32_e64 v204, s[4:5], s4, v196
	v_permlane32_swap_b32_e32 v80, v82
	v_permlane32_swap_b32_e32 v81, v83
	v_mfma_f32_32x32x16_bf16 v[84:99], v[184:187], v[150:153], v[84:99]
	v_addc_co_u32_e64 v205, s[4:5], 0, v197, s[4:5]
	global_load_dwordx4 v[178:181], v[132:133], off
	global_load_dwordx4 v[182:185], v[202:203], off
	global_load_dwordx4 v[186:189], v[204:205], off offset:2048
	s_waitcnt lgkmcnt(6)
	v_mfma_f32_32x32x16_bf16 v[50:65], v[76:79], v[134:137], v[50:65]
	ds_read_b64_tr_b16 v[134:135], v223 offset:0x1000
	ds_read_b64_tr_b16 v[136:137], v223 offset:0x1800
	v_exp_f32_e32 v68, v100
	v_exp_f32_e32 v69, v101
	v_add_f32_e32 v0, v68, v0
	s_waitcnt lgkmcnt(6)
	v_mfma_f32_32x32x16_bf16 v[34:49], v[76:79], v[138:141], v[34:49]
	ds_read_b64_tr_b16 v[138:139], v223 offset:0x1200
	ds_read_b64_tr_b16 v[140:141], v223 offset:0x1a00
	v_exp_f32_e32 v70, v102
	v_add_f32_e32 v0, v69, v0
	v_exp_f32_e32 v71, v103
	v_add_f32_e32 v0, v70, v0
	s_waitcnt lgkmcnt(6)
	v_mfma_f32_32x32x16_bf16 v[18:33], v[76:79], v[142:145], v[18:33]
	ds_read_b64_tr_b16 v[142:143], v223 offset:0x1400
	ds_read_b64_tr_b16 v[144:145], v223 offset:0x1c00
	v_exp_f32_e32 v72, v104
	v_add_f32_e32 v0, v71, v0
	v_exp_f32_e32 v73, v105
	v_add_f32_e32 v0, v72, v0
	s_waitcnt lgkmcnt(6)
; #define SBAR() __builtin_amdgcn_sched_barrier(0)
; template <bool FIRST> __device__ __forceinline__ void partialSM(f32x16& p0, f32x16& p1, float& m_reg, float& alpha, f32x16& negm, float c_cur) {
;   float pmax = p0[0];
; #pragma unroll
;   for (int r = 1; r < 16; ++r) pmax = fmaxf(pmax, p0[r]);
; #pragma unroll
;   for (int r = 0; r < 16; ++r) pmax = fmaxf(pmax, p1[r]);
;   { auto rr = __builtin_amdgcn_permlane32_swap(__float_as_uint(pmax), __float_as_uint(pmax), false, false);
;     pmax = fmaxf(__uint_as_float(rr[0]), __uint_as_float(rr[1])); }
; template <int OFF> __device__ __forceinline__ s16x4 tr_read(int vb) {
;   s16x4 r; asm volatile("ds_read_b64_tr_b16 %0, %1 offset:%2" : "=&v"(r) : "v"(vb), "i"(OFF) : "memory"); return r;
; }
; template <int D0> __device__ __forceinline__ void pv_one(f32x16& od, int vb, bf16x8 pa0, bf16x8 pa1, bf16x8 pa2, bf16x8 pa3) {
;   const s16x4 l0 = tr_read<v_rd_off(D0, 0, 0)>(vb), h0 = tr_read<v_rd_off(D0, 0, 1)>(vb), l1 = tr_read<v_rd_off(D0, 1, 0)>(vb), h1 = tr_read<v_rd_off(D0, 1, 1)>(vb);
;   const s16x4 l2 = tr_read<v_rd_off(D0, 2, 0)>(vb), h2 = tr_read<v_rd_off(D0, 2, 1)>(vb), l3 = tr_read<v_rd_off(D0, 3, 0)>(vb), h3 = tr_read<v_rd_off(D0, 3, 1)>(vb);
;   asm volatile("s_waitcnt lgkmcnt(0)" ::: "memory"); SBAR();
;     ...
;   od = __builtin_amdgcn_mfma_f32_32x32x16_bf16(pa0, PK(l0, h0), od, 0, 0, 0);
;   od = __builtin_amdgcn_mfma_f32_32x32x16_bf16(pa1, PK(l1, h1), od, 0, 0, 0);
;   od = __builtin_amdgcn_mfma_f32_32x32x16_bf16(pa2, PK(l2, h2), od, 0, 0, 0);
;   od = __builtin_amdgcn_mfma_f32_32x32x16_bf16(pa3, PK(l3, h3), od, 0, 0, 0);
;     ...
; }
; __device__ __forceinline__ void pv_d0(f32x16* o, int vb, bf16x8 pa0, bf16x8 pa1, bf16x8 pa2, bf16x8 pa3) {
;   pv_one<0>(o[0], vb, pa0, pa1, pa2, pa3); pv_one<1>(o[1], vb, pa0, pa1, pa2, pa3); pv_one<2>(o[2], vb, pa0, pa1, pa2, pa3); pv_one<3>(o[3], vb, pa0, pa1, pa2, pa3);
; }
	v_mfma_f32_32x32x16_bf16 v[2:17], v[76:79], v[198:201], v[2:17]
	ds_read_b64_tr_b16 v[198:199], v223 offset:0x1600
	ds_read_b64_tr_b16 v[200:201], v223 offset:0x1e00
	v_exp_f32_e32 v74, v106
	v_add_f32_e32 v0, v73, v0
	v_exp_f32_e32 v75, v107
	v_add_f32_e32 v0, v74, v0
	v_add_f32_e32 v0, v75, v0
	s_waitcnt lgkmcnt(6)
	v_mfma_f32_32x32x16_bf16 v[50:65], v[80:83], v[134:137], v[50:65]
	ds_read_b64_tr_b16 v[134:135], v223 offset:0x2000
	ds_read_b64_tr_b16 v[136:137], v223 offset:0x2800
	v_cvt_pk_bf16_f32 v100, v68, v69
	v_cvt_pk_bf16_f32 v101, v70, v71
	v_cvt_pk_bf16_f32 v102, v72, v73
	v_cvt_pk_bf16_f32 v103, v74, v75
	s_waitcnt lgkmcnt(6)
	v_mfma_f32_32x32x16_bf16 v[34:49], v[80:83], v[138:141], v[34:49]
	ds_read_b64_tr_b16 v[138:139], v223 offset:0x2200
	ds_read_b64_tr_b16 v[140:141], v223 offset:0x2a00
	v_exp_f32_e32 v68, v108
	v_exp_f32_e32 v69, v109
	v_permlane32_swap_b32_e32 v100, v102
	v_permlane32_swap_b32_e32 v101, v103
	s_waitcnt lgkmcnt(6)
	v_mfma_f32_32x32x16_bf16 v[18:33], v[80:83], v[142:145], v[18:33]
	ds_read_b64_tr_b16 v[142:143], v223 offset:0x2400
	ds_read_b64_tr_b16 v[144:145], v223 offset:0x2c00
	v_exp_f32_e32 v70, v110
	v_exp_f32_e32 v71, v111
	v_exp_f32_e32 v72, v112
	s_waitcnt lgkmcnt(6)
	v_mfma_f32_32x32x16_bf16 v[2:17], v[80:83], v[198:201], v[2:17]
	ds_read_b64_tr_b16 v[198:199], v223 offset:0x2600
	ds_read_b64_tr_b16 v[200:201], v223 offset:0x2e00
	v_exp_f32_e32 v73, v113
	v_exp_f32_e32 v74, v114
	v_exp_f32_e32 v75, v115
	s_waitcnt lgkmcnt(6)
	v_mfma_f32_32x32x16_bf16 v[50:65], v[100:103], v[134:137], v[50:65]
	ds_read_b64_tr_b16 v[134:135], v223 offset:0x3000
	ds_read_b64_tr_b16 v[136:137], v223 offset:0x3800
	v_add_f32_e32 v0, v68, v0
	v_add_f32_e32 v0, v69, v0
	v_add_f32_e32 v0, v70, v0
	v_add_f32_e32 v0, v71, v0
	s_waitcnt lgkmcnt(6)
	v_mfma_f32_32x32x16_bf16 v[34:49], v[100:103], v[138:141], v[34:49]
	ds_read_b64_tr_b16 v[138:139], v223 offset:0x3200
	ds_read_b64_tr_b16 v[140:141], v223 offset:0x3a00
	v_add_f32_e32 v0, v72, v0
	v_add_f32_e32 v0, v73, v0
	v_add_f32_e32 v0, v74, v0
	v_add_f32_e32 v0, v75, v0
	v_mov_b32_e32 v231, v0
	s_waitcnt lgkmcnt(6)
	v_mfma_f32_32x32x16_bf16 v[18:33], v[100:103], v[142:145], v[18:33]
	ds_read_b64_tr_b16 v[142:143], v223 offset:0x3400
	ds_read_b64_tr_b16 v[144:145], v223 offset:0x3c00
	v_cvt_pk_bf16_f32 v104, v68, v69
	v_cvt_pk_bf16_f32 v105, v70, v71
	v_cvt_pk_bf16_f32 v106, v72, v73
	v_cvt_pk_bf16_f32 v107, v74, v75
	v_permlane32_swap_b32_e32 v0, v231
	s_waitcnt lgkmcnt(6)
	v_mfma_f32_32x32x16_bf16 v[2:17], v[100:103], v[198:201], v[2:17]
	ds_read_b64_tr_b16 v[198:199], v223 offset:0x3600
	ds_read_b64_tr_b16 v[200:201], v223 offset:0x3e00
	v_permlane32_swap_b32_e32 v104, v106
	v_permlane32_swap_b32_e32 v105, v107
	v_max_f32_e32 v132, v84, v85
	v_max3_f32 v132, v132, v86, v87
	v_max3_f32 v132, v132, v88, v89
	s_waitcnt lgkmcnt(6)
	v_mfma_f32_32x32x16_bf16 v[50:65], v[104:107], v[134:137], v[50:65]
	v_max3_f32 v132, v132, v90, v91
	v_max3_f32 v132, v132, v92, v93
	v_max3_f32 v132, v132, v94, v95
	v_max3_f32 v132, v132, v96, v97
	v_max3_f32 v132, v132, v98, v99
	s_waitcnt lgkmcnt(4)
	v_mfma_f32_32x32x16_bf16 v[34:49], v[104:107], v[138:141], v[34:49]
	v_max3_f32 v132, v132, v116, v117
	v_max3_f32 v132, v132, v118, v119
	v_max3_f32 v132, v132, v120, v121
	v_max3_f32 v132, v132, v122, v123
	v_max3_f32 v132, v132, v124, v125
	s_waitcnt lgkmcnt(2)
	v_mfma_f32_32x32x16_bf16 v[18:33], v[104:107], v[142:145], v[18:33]
	v_max3_f32 v132, v132, v126, v127
	v_max3_f32 v132, v132, v128, v129
	v_max3_f32 v132, v132, v130, v131
	v_mov_b32_e32 v133, v132
	s_waitcnt lgkmcnt(0)
	v_mfma_f32_32x32x16_bf16 v[2:17], v[104:107], v[198:201], v[2:17]
	v_permlane32_swap_b32_e32 v132, v133
	v_max_f32_e32 v100, v132, v133
	s_branch .Ljoin_h1

; __device__ __forceinline__ void finishSM(f32x16& p0, f32x16& p1, float alpha, float& l_reg, bf16x8& pa0, bf16x8& pa1, bf16x8& pa2, bf16x8& pa3) {
; #pragma unroll
;   for (int r = 0; r < 16; ++r) p1[r] = __builtin_amdgcn_exp2f(p1[r]);
;   float ps = 0;
; #pragma unroll
;   for (int r = 0; r < 16; ++r) ps += p0[r];
; #pragma unroll
;   for (int r = 0; r < 16; ++r) ps += p1[r];
;   { auto rr = __builtin_amdgcn_permlane32_swap(__float_as_uint(ps), __float_as_uint(ps), false, false);
;     ps = __uint_as_float(rr[0]) + __uint_as_float(rr[1]); }
;   l_reg = l_reg * alpha + ps;
;     ...
;   PK4(p0, 0, pa0); PK4(p0, 8, pa1); PK4(p1, 0, pa2); PK4(p1, 8, pa3);
;     ...
; }
; template <int DQK> __device__ __forceinline__ void qkt(f32x16& p0, f32x16& p1, const char* Ks, const bf16x8* qr, int r32, int hi, const f32x16& negm) {
; #pragma unroll
;   for (int d0 = 0; d0 < DQK / 16; ++d0) { const int cb = (d0 * 16 + hi * 8) * 2;
;     const bf16x8 b0 = *reinterpret_cast<const bf16x8*>(Ks + (DQK == 128 ? KSWZ(r32, cb) : KSWZ64(r32, cb)));
;     const bf16x8 b1 = *reinterpret_cast<const bf16x8*>(Ks + (DQK == 128 ? KSWZ(32 + r32, cb) : KSWZ64(32 + r32, cb)));
;     if (d0 == 0) { p0 = __builtin_amdgcn_mfma_f32_32x32x16_bf16(b0, qr[0], negm, 0, 0, 0); p1 = __builtin_amdgcn_mfma_f32_32x32x16_bf16(b1, qr[0], negm, 0, 0, 0); }
;     else { p0 = __builtin_amdgcn_mfma_f32_32x32x16_bf16(b0, qr[d0], p0, 0, 0, 0); p1 = __builtin_amdgcn_mfma_f32_32x32x16_bf16(b1, qr[d0], p1, 0, 0, 0); } }
; }
; __device__ __forceinline__ int v_st(int k, int c) { const int kk = (k & ~0xC) | ((k & 4) << 1) | ((k & 8) >> 1); return ((kk >> 3) * 4 + (c >> 5)) * 512 + ((kk & 7) * 32 + (c & 31)) * 2; }
; __device__ __forceinline__ int v_rd_base(int lane) { return ((lane & 3) << 3) | (((lane >> 2) & 3) << 6) | (((lane >> 4) & 1) << 5) | (((lane >> 5) & 1) << 8); }
; template <int OFF> __device__ __forceinline__ s16x4 tr_read(int vb) {
;   s16x4 r; asm volatile("ds_read_b64_tr_b16 %0, %1 offset:%2" : "=&v"(r) : "v"(vb), "i"(OFF) : "memory"); return r;
; }
; template <int D0> __device__ __forceinline__ void pv_one(f32x16& od, int vb, bf16x8 pa0, bf16x8 pa1, bf16x8 pa2, bf16x8 pa3) {
;   const s16x4 l0 = tr_read<v_rd_off(D0, 0, 0)>(vb), h0 = tr_read<v_rd_off(D0, 0, 1)>(vb), l1 = tr_read<v_rd_off(D0, 1, 0)>(vb), h1 = tr_read<v_rd_off(D0, 1, 1)>(vb);
.Lcret_f2:
	s_waitcnt lgkmcnt(4)
	v_mfma_f32_32x32x16_bf16 v[68:83], v[100:103], v[162:165], v[236:251]
	v_mfma_f32_32x32x16_bf16 v[100:115], v[84:87], v[162:165], v[236:251]
	ds_read_b128 v[84:87], v226 offset:36864
	v_add_f32_e32 v235, 0, v219
	v_add_f32_e32 v235, v233, v235
	v_add_f32_e32 v235, v209, v235
	v_add_f32_e32 v235, v220, v235
	v_add_f32_e32 v235, v207, v235
	v_add_f32_e32 v235, v218, v235
	v_add_f32_e32 v235, v206, v235
	v_add_f32_e32 v235, v208, v235
	v_add_f32_e32 v235, v203, v235
	v_add_f32_e32 v235, v205, v235
	s_waitcnt lgkmcnt(3)
	v_mfma_f32_32x32x16_bf16 v[100:115], v[88:91], v[158:161], v[100:115]
	v_add_f32_e32 v235, v201, v235
	v_add_f32_e32 v235, v204, v235
	v_add_f32_e32 v235, v199, v235
	v_add_f32_e32 v235, v202, v235
	v_add_f32_e32 v235, v198, v235
	v_add_f32_e32 v235, v200, v235
	v_mfma_f32_32x32x16_bf16 v[68:83], v[134:137], v[158:161], v[68:83]
	ds_read_b128 v[88:91], v226 offset:32768
	v_cvt_pk_bf16_f32 v92, v219, v233
	v_cvt_pk_bf16_f32 v93, v209, v220
	v_cvt_pk_bf16_f32 v94, v207, v218
	v_cvt_pk_bf16_f32 v95, v206, v208
	v_add_co_u32_e32 v132, vcc, 0x10341000, v148
	s_waitcnt lgkmcnt(2)
	v_mfma_f32_32x32x16_bf16 v[100:115], v[138:141], v[154:157], v[100:115]
	v_cvt_pk_bf16_f32 v96, v203, v205
	v_cvt_pk_bf16_f32 v97, v201, v204
	v_addc_co_u32_e32 v133, vcc, 0, v149, vcc
	v_add_co_u32_e32 v174, vcc, 0x10389000, v148
	v_cvt_pk_bf16_f32 v98, v199, v202
	v_cvt_pk_bf16_f32 v99, v198, v200
	v_addc_co_u32_e32 v175, vcc, 0, v149, vcc
	v_mfma_f32_32x32x16_bf16 v[68:83], v[142:145], v[154:157], v[68:83]
	ds_read_b64_tr_b16 v[134:135], v211 offset:0
	ds_read_b64_tr_b16 v[136:137], v211 offset:0x800
	ds_read_b64_tr_b16 v[138:139], v211 offset:0x200
	ds_read_b64_tr_b16 v[140:141], v211 offset:0xa00
	ds_read_b64_tr_b16 v[142:143], v211 offset:0x400
	ds_read_b64_tr_b16 v[144:145], v211 offset:0xc00
	ds_read_b64_tr_b16 v[146:147], v211 offset:0x600
	ds_read_b64_tr_b16 v[148:149], v211 offset:0xe00
	v_permlane32_swap_b32_e32 v92, v94
	v_permlane32_swap_b32_e32 v93, v95
	v_add_co_u32_e32 v176, vcc, 0x10340000, v196
	s_waitcnt lgkmcnt(8)
	v_mfma_f32_32x32x16_bf16 v[100:115], v[84:87], v[150:153], v[100:115]
	v_permlane32_swap_b32_e32 v96, v98
	v_permlane32_swap_b32_e32 v97, v99
	v_mfma_f32_32x32x16_bf16 v[68:83], v[88:91], v[150:153], v[68:83]
	v_addc_co_u32_e32 v177, vcc, 0, v197, vcc
	s_cmp_ge_u32 s4, s28
	s_cbranch_scc1 .Lnold_h2
	global_load_dwordx4 v[166:169], v[132:133], off
	global_load_dwordx4 v[170:173], v[174:175], off
	global_load_dwordx4 v[174:177], v[176:177], off offset:2048
